# E1 gain-load hoist + E4 compact forget-gate log_sigmoid + E6 batched loads in prologue weight transposes + E5 lane-parallel band gain scan + E7 first seam uses xcd barrier
# speedup vs baseline: 1.0138x; 1.0138x over previous
.LBB0_83:
	v_lshl_add_u64 v[52:53], v[48:49], 0, s[16:17]
	global_load_dword v121, v[52:53], off
	v_lshl_add_u64 v[52:53], v[46:47], 0, s[16:17]
	global_load_dword v122, v[52:53], off
	v_lshl_add_u64 v[52:53], v[44:45], 0, s[16:17]
	global_load_dword v123, v[52:53], off
	v_lshl_add_u64 v[52:53], v[42:43], 0, s[16:17]
	global_load_dword v124, v[52:53], off
	v_lshl_add_u64 v[52:53], v[40:41], 0, s[16:17]
	global_load_dword v125, v[52:53], off
	v_lshl_add_u64 v[52:53], v[38:39], 0, s[16:17]
	global_load_dword v126, v[52:53], off
	v_lshl_add_u64 v[52:53], v[36:37], 0, s[16:17]
	global_load_dword v127, v[52:53], off
	v_lshl_add_u64 v[52:53], v[32:33], 0, s[16:17]
	global_load_dword v128, v[52:53], off
	s_andn2_b64 vcc, exec, s[36:37]
	s_cbranch_vccnz .Ltr_in_nogain
	v_lshl_add_u64 v[52:53], s[18:19], 0, v[50:51]
	global_load_dword v129, v[52:53], off offset:-56
	v_lshl_add_u64 v[52:53], s[18:19], 0, v[34:35]
	global_load_dword v130, v[52:53], off offset:-48
	global_load_dword v131, v[52:53], off offset:-40
	global_load_dword v132, v[52:53], off offset:-32
	global_load_dword v133, v[52:53], off offset:-24
	global_load_dword v134, v[52:53], off offset:-16
	global_load_dword v135, v[52:53], off offset:-8
	global_load_dword v136, v[52:53], off
	s_waitcnt vmcnt(0)
	v_mul_f32_e32 v121, v121, v129
	v_mul_f32_e32 v122, v122, v130
	v_mul_f32_e32 v123, v123, v131
	v_mul_f32_e32 v124, v124, v132
	v_mul_f32_e32 v125, v125, v133
	v_mul_f32_e32 v126, v126, v134
	v_mul_f32_e32 v127, v127, v135
	v_mul_f32_e32 v128, v128, v136
.Ltr_in_nogain:
	s_waitcnt vmcnt(0)
	v_mul_f32_e32 v121, v29, v121
	v_mul_f32_e32 v122, v29, v122
	v_mul_f32_e32 v123, v29, v123
	v_mul_f32_e32 v124, v29, v124
	v_mul_f32_e32 v125, v29, v125
	v_mul_f32_e32 v126, v29, v126
	v_mul_f32_e32 v127, v29, v127
	v_mul_f32_e32 v128, v29, v128
	ds_write_b32 v65, v121
	ds_write_b32 v65, v122 offset:264
	ds_write_b32 v65, v123 offset:528
	ds_write_b32 v65, v124 offset:792
	ds_write_b32 v65, v125 offset:1056
	ds_write_b32 v65, v126 offset:1320
	ds_write_b32 v65, v127 offset:1584
	ds_write_b32 v65, v128 offset:1848
	s_add_u32 s16, s16, 0x58000
	s_addc_u32 s17, s17, 0
	s_add_u32 s18, s18, 64
	s_addc_u32 s19, s19, 0
	v_add_u32_e32 v65, 0x840, v65
	s_cmp_lg_u32 s16, 0x160000
	s_cbranch_scc1 .LBB0_83

.LBB0_119:
	v_lshl_add_u64 v[50:51], v[32:33], 0, s[12:13]
	global_load_dword v121, v[50:51], off
	v_lshl_add_u64 v[50:51], v[46:47], 0, s[12:13]
	global_load_dword v122, v[50:51], off
	v_lshl_add_u64 v[50:51], v[44:45], 0, s[12:13]
	global_load_dword v123, v[50:51], off
	v_lshl_add_u64 v[50:51], v[42:43], 0, s[12:13]
	global_load_dword v124, v[50:51], off
	v_lshl_add_u64 v[50:51], v[40:41], 0, s[12:13]
	global_load_dword v125, v[50:51], off
	v_lshl_add_u64 v[50:51], v[38:39], 0, s[12:13]
	global_load_dword v126, v[50:51], off
	v_lshl_add_u64 v[50:51], v[34:35], 0, s[12:13]
	global_load_dword v127, v[50:51], off
	v_lshl_add_u64 v[50:51], v[30:31], 0, s[12:13]
	global_load_dword v128, v[50:51], off
	v_readlane_b32 s18, v251, 23
	v_readlane_b32 s19, v251, 24
	s_andn2_b64 vcc, exec, s[18:19]
	s_cbranch_vccnz .Ltr_qkv_nogain
	global_load_dword v129, v[36:37], off offset:-56
	global_load_dword v130, v[36:37], off offset:-48
	global_load_dword v131, v[36:37], off offset:-40
	global_load_dword v132, v[36:37], off offset:-32
	global_load_dword v133, v[36:37], off offset:-24
	global_load_dword v134, v[36:37], off offset:-16
	global_load_dword v135, v[36:37], off offset:-8
	global_load_dword v136, v[36:37], off
	s_waitcnt vmcnt(0)
	v_mul_f32_e32 v121, v121, v129
	v_mul_f32_e32 v122, v122, v130
	v_mul_f32_e32 v123, v123, v131
	v_mul_f32_e32 v124, v124, v132
	v_mul_f32_e32 v125, v125, v133
	v_mul_f32_e32 v126, v126, v134
	v_mul_f32_e32 v127, v127, v135
	v_mul_f32_e32 v128, v128, v136
.Ltr_qkv_nogain:
	s_waitcnt vmcnt(0)
	ds_write_b32 v29, v121
	ds_write_b32 v29, v122 offset:264
	ds_write_b32 v29, v123 offset:528
	ds_write_b32 v29, v124 offset:792
	ds_write_b32 v29, v125 offset:1056
	ds_write_b32 v29, v126 offset:1320
	ds_write_b32 v29, v127 offset:1584
	ds_write_b32 v29, v128 offset:1848
	s_add_u32 s12, s12, 0x90000
	s_addc_u32 s13, s13, 0
	v_add_u32_e32 v29, 0x840, v29
	v_lshl_add_u64 v[36:37], v[36:37], 0, 64
	s_cmp_lg_u32 s12, 0x240000
	s_cbranch_scc1 .LBB0_119

.LBB0_520:
	v_cmp_gt_u32_e32 vcc, 48, v203
	v_lshlrev_b32_e32 v2, 4, v203
	s_and_saveexec_b64 s[2:3], vcc
	s_waitcnt lgkmcnt(0)
	global_load_dwordx4 v[4:7], v2, s[18:19]
	global_load_dwordx4 v[8:11], v2, s[52:53]
	s_waitcnt vmcnt(0)
	v_max3_f32 v1, |v4|, |v5|, |v6|
	v_max3_f32 v0, |v8|, |v9|, |v10|
	v_max_f32_e64 v1, v1, |v7|
	v_max_f32_e64 v0, v0, |v11|
	s_or_b64 exec, exec, s[2:3]
	v_mov_b32_e32 v2, v1
	v_mov_b32_e32 v3, v0
	s_nop 1
	v_permlane32_swap_b32_e32 v1, v2
	v_permlane32_swap_b32_e32 v0, v3
	v_max_f32_e32 v1, v1, v2
	v_max_f32_e32 v0, v0, v3
	v_mov_b32_e32 v2, v1
	v_mov_b32_e32 v3, v0
	s_nop 1
	v_permlane16_swap_b32_e32 v1, v2
	v_permlane16_swap_b32_e32 v0, v3
	v_max_f32_e32 v1, v1, v2
	v_max_f32_e32 v0, v0, v3
	s_nop 1
	v_readlane_b32 s2, v1, 0
	v_readlane_b32 s3, v0, 0
	v_readlane_b32 s0, v1, 1
	s_max_u32 s2, s2, s0
	v_readlane_b32 s1, v0, 1
	s_max_u32 s3, s3, s1
	v_readlane_b32 s0, v1, 2
	s_max_u32 s2, s2, s0
	v_readlane_b32 s1, v0, 2
	s_max_u32 s3, s3, s1
	v_readlane_b32 s0, v1, 3
	s_max_u32 s2, s2, s0
	v_readlane_b32 s1, v0, 3
	s_max_u32 s3, s3, s1
	v_readlane_b32 s0, v1, 4
	s_max_u32 s2, s2, s0
	v_readlane_b32 s1, v0, 4
	s_max_u32 s3, s3, s1
	v_readlane_b32 s0, v1, 5
	s_max_u32 s2, s2, s0
	v_readlane_b32 s1, v0, 5
	s_max_u32 s3, s3, s1
	v_readlane_b32 s0, v1, 6
	s_max_u32 s2, s2, s0
	v_readlane_b32 s1, v0, 6
	s_max_u32 s3, s3, s1
	v_readlane_b32 s0, v1, 7
	s_max_u32 s2, s2, s0
	v_readlane_b32 s1, v0, 7
	s_max_u32 s3, s3, s1
	v_readlane_b32 s0, v1, 8
	s_max_u32 s2, s2, s0
	v_readlane_b32 s1, v0, 8
	s_max_u32 s3, s3, s1
	v_readlane_b32 s0, v1, 9
	s_max_u32 s2, s2, s0
	v_readlane_b32 s1, v0, 9
	s_max_u32 s3, s3, s1
	v_readlane_b32 s0, v1, 10
	s_max_u32 s2, s2, s0
	v_readlane_b32 s1, v0, 10
	s_max_u32 s3, s3, s1
	v_readlane_b32 s0, v1, 11
	s_max_u32 s2, s2, s0
	v_readlane_b32 s1, v0, 11
	s_max_u32 s3, s3, s1
	v_readlane_b32 s0, v1, 12
	s_max_u32 s2, s2, s0
	v_readlane_b32 s1, v0, 12
	s_max_u32 s3, s3, s1
	v_readlane_b32 s0, v1, 13
	s_max_u32 s2, s2, s0
	v_readlane_b32 s1, v0, 13
	s_max_u32 s3, s3, s1
	v_readlane_b32 s0, v1, 14
	s_max_u32 s2, s2, s0
	v_readlane_b32 s1, v0, 14
	s_max_u32 s3, s3, s1
	v_readlane_b32 s0, v1, 15
	s_max_u32 s2, s2, s0
	v_readlane_b32 s1, v0, 15
	s_max_u32 s3, s3, s1
	v_mov_b32_e32 v1, s2
	v_mov_b32_e32 v0, s3
	v_mul_f32_e32 v1, 0x4138aa3b, v1
	v_mul_f32_e32 v0, v0, v1
	s_mov_b32 s0, 0x3f83d70a
	v_fma_f32 v0, v0, s0, 0.5
	s_mov_b32 s0, 0x42700000
	v_cmp_gt_f32_e64 s[0:1], s0, v0

.LBB0_1043:
	v_readlane_b32 s2, v254, 18
	s_cmp_lg_u32 s2, 0x7f
	s_mov_b64 s[0:1], -1
	s_cselect_b64 s[2:3], -1, 0
	s_andn2_b64 vcc, exec, s[2:3]
	s_mov_b64 s[2:3], 0
	s_cbranch_vccnz .LBB0_1040
